# v33 + grid barrier: non-leader workgroups poll the cross-XCD generation word directly (one release hop instead of two)
# baseline (speedup 1.0000x reference)
.LBB0_1073:
	s_or_b64 exec, exec, s[10:11]
	v_cvt_f32_u32_e32 v5, v3
	s_waitcnt vmcnt(0)
	v_readfirstlane_b32 s2, v4
	v_sub_u32_e32 v4, 0, v3
	v_rcp_iflag_f32_e32 v5, v5
	v_add_u32_e32 v6, s2, v1
	v_mul_f32_e32 v5, 0x4f7ffffe, v5
	v_cvt_u32_f32_e32 v5, v5
	v_mul_lo_u32 v1, v4, v5
	v_mul_hi_u32 v1, v5, v1
	v_add_u32_e32 v1, v5, v1
	v_mul_hi_u32 v1, v6, v1
	v_mul_lo_u32 v4, v1, v3
	v_sub_u32_e32 v4, v6, v4
	v_add_u32_e32 v5, 1, v1
	v_cmp_ge_u32_e32 vcc, v4, v3
	s_nop 1
	v_cndmask_b32_e32 v1, v1, v5, vcc
	v_sub_u32_e32 v5, v4, v3
	v_cndmask_b32_e32 v4, v4, v5, vcc
	v_add_u32_e32 v5, 1, v1
	v_cmp_ge_u32_e32 vcc, v4, v3
	v_add_u32_e32 v4, 1, v6
	s_nop 0
	v_cndmask_b32_e32 v1, v1, v5, vcc
	v_mul_lo_u32 v5, v3, v1
	v_add_u32_e32 v3, v5, v3
	v_cmp_ne_u32_e32 vcc, v4, v3
	s_and_saveexec_b64 s[6:7], vcc
	s_xor_b64 s[10:11], exec, s[6:7]
	s_cbranch_execz .LBB0_1087
	s_waitcnt lgkmcnt(0)
	v_readlane_b32 s98, v254, 37
	v_readlane_b32 s99, v254, 38
	s_nop 4
	global_load_dword v2, v0, s[98:99] sc1
	s_waitcnt vmcnt(0)
	v_cmp_eq_u32_e32 vcc, v2, v1
	s_and_saveexec_b64 s[18:19], vcc
	s_cbranch_execz .LBB0_1086
	s_mov_b32 s2, 1
	s_mov_b64 s[20:21], 0
	s_branch .LBB0_1077

.LBB0_1079:
	global_load_dword v2, v0, s[98:99] sc1
	s_add_i32 s2, s2, 1
	s_mov_b64 s[38:39], -1
	s_waitcnt vmcnt(0)
	v_cmp_ne_u32_e32 vcc, v2, v1
	s_orn2_b64 s[36:37], vcc, exec
	s_branch .LBB0_1076
